# output projections: main GEMM covers the 1024 prompt tiles (4 per workgroup, no fifth round); the 512 sample rows are computed by a small direct-from-global MFMA tile per workgroup
# speedup vs baseline: 1.0136x; 1.0005x over previous
; __device__ __forceinline__ u32x2 pk4(const f32x4 v) { return (u32x2){pk_bf16(v[0], v[1]), pk_bf16(v[2], v[3])}; }
; __device__ __forceinline__ void st8_bf16(bf16_t* p, const f32x4 a, const f32x4 b) { __builtin_nontemporal_store((u32x4){pk_bf16(a[0], a[1]), pk_bf16(a[2], a[3]), pk_bf16(b[0], b[1]), pk_bf16(b[2], b[3])}, (u32x4*)p); }
;     __device__ __forceinline__ void store8(int row, int col, const f32x4 v, const f32x4 w) const { store4(row, col, v); store4(row, col + 4, w); }
; #define PH(n) if ((n) > a.ph_lo && (n) < a.ph_hi) cg::this_grid().sync(); if ((n) >= a.ph_lo && (n) < a.ph_hi)
;     __device__ __forceinline__ void store4(int row, int col, const f32x4 v) const { __builtin_nontemporal_store(pk4(v), (u32x2*)((bf16_t*)((unsigned char*)out + T_D0) + (size_t)row * DM + col)); }
;     __device__ __forceinline__ void store8(int row, int col, const f32x4 v, const f32x4 w) const { st8_bf16((bf16_t*)((unsigned char*)out + T_D0) + (size_t)row * DM + col, v, w); }
; __global__ void __launch_bounds__(NTHR) mega(Args a) {
;     ...
;     PH(4) { const Args A = load_args(); unsigned char* ws = A.ws; unsigned char* ob = (unsigned char*)A.out; (void)ws; (void)ob; EpiOut0 E{A.out};
;             gemm_pg8(lds, (const bf16_t*)(ws + WS_BRANCH), (const bf16_t*)(ws + WS_WOUT_T), MT, 1024, 2048, E); }
.LBB0_672:
	s_cmp_lt_i32 s48, 5
	s_cselect_b64 s[6:7], -1, 0
	s_and_b64 s[4:5], s[6:7], s[4:5]
	s_andn2_b64 vcc, exec, s[4:5]
	s_cbranch_vccnz .LBB0_689
	s_load_dwordx4 s[84:87], s[0:1], 0x100
	v_and_b32_e32 v0, 15, v170
	v_bfe_u32 v1, v170, 4, 2
	v_bfe_u32 v2, v170, 6, 2
	v_lshrrev_b32_e32 v3, 8, v170
	v_lshl_add_u32 v4, v2, 4, v0
	v_lshlrev_b32_e32 v4, 12, v4
	v_lshl_add_u32 v4, v1, 4, v4
	v_lshl_add_u32 v5, v3, 4, v0
	v_lshlrev_b32_e32 v6, 12, v5
	v_lshl_add_u32 v6, v1, 4, v6
	s_lshr_b32 s88, s2, 4
	s_and_b32 s89, s2, 15
	s_waitcnt lgkmcnt(0)
	s_lshl_b32 s90, s89, 18
	s_add_u32 s92, s86, 0x1c80000
	s_addc_u32 s93, s87, 0
	s_add_u32 s92, s92, s90
	s_addc_u32 s93, s93, 0
	s_lshl_b32 s90, s88, 17
	s_add_u32 s94, s86, 0x58e0000
	s_addc_u32 s95, s87, 0
	s_add_u32 s94, s94, 0x10000000
	s_addc_u32 s95, s95, 0
	s_add_u32 s94, s94, s90
	s_addc_u32 s95, s95, 0
	global_load_dwordx4 v[16:19], v4, s[92:93] offset:0
	global_load_dwordx4 v[20:23], v6, s[94:95] offset:0
	global_load_dwordx4 v[24:27], v4, s[92:93] offset:64
	global_load_dwordx4 v[28:31], v6, s[94:95] offset:64
	global_load_dwordx4 v[32:35], v4, s[92:93] offset:128
	global_load_dwordx4 v[36:39], v6, s[94:95] offset:128
	global_load_dwordx4 v[40:43], v4, s[92:93] offset:192
	global_load_dwordx4 v[44:47], v6, s[94:95] offset:192
	global_load_dwordx4 v[48:51], v4, s[92:93] offset:256
	global_load_dwordx4 v[52:55], v6, s[94:95] offset:256
	global_load_dwordx4 v[56:59], v4, s[92:93] offset:320
	global_load_dwordx4 v[60:63], v6, s[94:95] offset:320
	global_load_dwordx4 v[64:67], v4, s[92:93] offset:384
	global_load_dwordx4 v[68:71], v6, s[94:95] offset:384
	global_load_dwordx4 v[72:75], v4, s[92:93] offset:448
	global_load_dwordx4 v[76:79], v6, s[94:95] offset:448
	global_load_dwordx4 v[80:83], v4, s[92:93] offset:512
	global_load_dwordx4 v[84:87], v6, s[94:95] offset:512
	global_load_dwordx4 v[88:91], v4, s[92:93] offset:576
	global_load_dwordx4 v[92:95], v6, s[94:95] offset:576
	global_load_dwordx4 v[96:99], v4, s[92:93] offset:640
	global_load_dwordx4 v[100:103], v6, s[94:95] offset:640
	global_load_dwordx4 v[104:107], v4, s[92:93] offset:704
	global_load_dwordx4 v[108:111], v6, s[94:95] offset:704
	global_load_dwordx4 v[112:115], v4, s[92:93] offset:768
	global_load_dwordx4 v[116:119], v6, s[94:95] offset:768
	global_load_dwordx4 v[120:123], v4, s[92:93] offset:832
	global_load_dwordx4 v[124:127], v6, s[94:95] offset:832
	global_load_dwordx4 v[128:131], v4, s[92:93] offset:896
	global_load_dwordx4 v[132:135], v6, s[94:95] offset:896
	global_load_dwordx4 v[136:139], v4, s[92:93] offset:960
	global_load_dwordx4 v[140:143], v6, s[94:95] offset:960
	s_waitcnt vmcnt(16)
	v_mfma_f32_16x16x32_bf16 v[8:11], v[16:19], v[20:23], 0
	v_mfma_f32_16x16x32_bf16 v[12:15], v[24:27], v[28:31], 0
	v_mfma_f32_16x16x32_bf16 v[8:11], v[32:35], v[36:39], v[8:11]
	v_mfma_f32_16x16x32_bf16 v[12:15], v[40:43], v[44:47], v[12:15]
	v_mfma_f32_16x16x32_bf16 v[8:11], v[48:51], v[52:55], v[8:11]
	v_mfma_f32_16x16x32_bf16 v[12:15], v[56:59], v[60:63], v[12:15]
	v_mfma_f32_16x16x32_bf16 v[8:11], v[64:67], v[68:71], v[8:11]
	v_mfma_f32_16x16x32_bf16 v[12:15], v[72:75], v[76:79], v[12:15]
	global_load_dwordx4 v[16:19], v4, s[92:93] offset:1024
	global_load_dwordx4 v[20:23], v6, s[94:95] offset:1024
	global_load_dwordx4 v[24:27], v4, s[92:93] offset:1088
	global_load_dwordx4 v[28:31], v6, s[94:95] offset:1088
	global_load_dwordx4 v[32:35], v4, s[92:93] offset:1152
	global_load_dwordx4 v[36:39], v6, s[94:95] offset:1152
	global_load_dwordx4 v[40:43], v4, s[92:93] offset:1216
	global_load_dwordx4 v[44:47], v6, s[94:95] offset:1216
	global_load_dwordx4 v[48:51], v4, s[92:93] offset:1280
	global_load_dwordx4 v[52:55], v6, s[94:95] offset:1280
	global_load_dwordx4 v[56:59], v4, s[92:93] offset:1344
	global_load_dwordx4 v[60:63], v6, s[94:95] offset:1344
	global_load_dwordx4 v[64:67], v4, s[92:93] offset:1408
	global_load_dwordx4 v[68:71], v6, s[94:95] offset:1408
	global_load_dwordx4 v[72:75], v4, s[92:93] offset:1472
	global_load_dwordx4 v[76:79], v6, s[94:95] offset:1472
	s_waitcnt vmcnt(16)
	v_mfma_f32_16x16x32_bf16 v[8:11], v[80:83], v[84:87], v[8:11]
	v_mfma_f32_16x16x32_bf16 v[12:15], v[88:91], v[92:95], v[12:15]
	v_mfma_f32_16x16x32_bf16 v[8:11], v[96:99], v[100:103], v[8:11]
	v_mfma_f32_16x16x32_bf16 v[12:15], v[104:107], v[108:111], v[12:15]
	v_mfma_f32_16x16x32_bf16 v[8:11], v[112:115], v[116:119], v[8:11]
	v_mfma_f32_16x16x32_bf16 v[12:15], v[120:123], v[124:127], v[12:15]
	v_mfma_f32_16x16x32_bf16 v[8:11], v[128:131], v[132:135], v[8:11]
	v_mfma_f32_16x16x32_bf16 v[12:15], v[136:139], v[140:143], v[12:15]
	global_load_dwordx4 v[80:83], v4, s[92:93] offset:1536
	global_load_dwordx4 v[84:87], v6, s[94:95] offset:1536
	global_load_dwordx4 v[88:91], v4, s[92:93] offset:1600
	global_load_dwordx4 v[92:95], v6, s[94:95] offset:1600
	global_load_dwordx4 v[96:99], v4, s[92:93] offset:1664
	global_load_dwordx4 v[100:103], v6, s[94:95] offset:1664
	global_load_dwordx4 v[104:107], v4, s[92:93] offset:1728
	global_load_dwordx4 v[108:111], v6, s[94:95] offset:1728
	global_load_dwordx4 v[112:115], v4, s[92:93] offset:1792
	global_load_dwordx4 v[116:119], v6, s[94:95] offset:1792
	global_load_dwordx4 v[120:123], v4, s[92:93] offset:1856
	global_load_dwordx4 v[124:127], v6, s[94:95] offset:1856
	global_load_dwordx4 v[128:131], v4, s[92:93] offset:1920
	global_load_dwordx4 v[132:135], v6, s[94:95] offset:1920
	global_load_dwordx4 v[136:139], v4, s[92:93] offset:1984
	global_load_dwordx4 v[140:143], v6, s[94:95] offset:1984
	s_waitcnt vmcnt(16)
; #define PH(n) if ((n) > a.ph_lo && (n) < a.ph_hi) cg::this_grid().sync(); if ((n) >= a.ph_lo && (n) < a.ph_hi)
; __global__ void __launch_bounds__(NTHR) mega(Args a) {
;     ...
;     PH(4) { const Args A = load_args(); unsigned char* ws = A.ws; unsigned char* ob = (unsigned char*)A.out; (void)ws; (void)ob; EpiOut0 E{A.out};
;             gemm_pg8(lds, (const bf16_t*)(ws + WS_BRANCH), (const bf16_t*)(ws + WS_WOUT_T), MT, 1024, 2048, E); }
	v_mfma_f32_16x16x32_bf16 v[8:11], v[16:19], v[20:23], v[8:11]
	v_mfma_f32_16x16x32_bf16 v[12:15], v[24:27], v[28:31], v[12:15]
	v_mfma_f32_16x16x32_bf16 v[8:11], v[32:35], v[36:39], v[8:11]
	v_mfma_f32_16x16x32_bf16 v[12:15], v[40:43], v[44:47], v[12:15]
	v_mfma_f32_16x16x32_bf16 v[8:11], v[48:51], v[52:55], v[8:11]
	v_mfma_f32_16x16x32_bf16 v[12:15], v[56:59], v[60:63], v[12:15]
	v_mfma_f32_16x16x32_bf16 v[8:11], v[64:67], v[68:71], v[8:11]
	v_mfma_f32_16x16x32_bf16 v[12:15], v[72:75], v[76:79], v[12:15]
	global_load_dwordx4 v[16:19], v4, s[92:93] offset:2048
	global_load_dwordx4 v[20:23], v6, s[94:95] offset:2048
	global_load_dwordx4 v[24:27], v4, s[92:93] offset:2112
	global_load_dwordx4 v[28:31], v6, s[94:95] offset:2112
	global_load_dwordx4 v[32:35], v4, s[92:93] offset:2176
	global_load_dwordx4 v[36:39], v6, s[94:95] offset:2176
	global_load_dwordx4 v[40:43], v4, s[92:93] offset:2240
	global_load_dwordx4 v[44:47], v6, s[94:95] offset:2240
	global_load_dwordx4 v[48:51], v4, s[92:93] offset:2304
	global_load_dwordx4 v[52:55], v6, s[94:95] offset:2304
	global_load_dwordx4 v[56:59], v4, s[92:93] offset:2368
	global_load_dwordx4 v[60:63], v6, s[94:95] offset:2368
	global_load_dwordx4 v[64:67], v4, s[92:93] offset:2432
	global_load_dwordx4 v[68:71], v6, s[94:95] offset:2432
	global_load_dwordx4 v[72:75], v4, s[92:93] offset:2496
	global_load_dwordx4 v[76:79], v6, s[94:95] offset:2496
	s_waitcnt vmcnt(16)
	v_mfma_f32_16x16x32_bf16 v[8:11], v[80:83], v[84:87], v[8:11]
	v_mfma_f32_16x16x32_bf16 v[12:15], v[88:91], v[92:95], v[12:15]
	v_mfma_f32_16x16x32_bf16 v[8:11], v[96:99], v[100:103], v[8:11]
	v_mfma_f32_16x16x32_bf16 v[12:15], v[104:107], v[108:111], v[12:15]
	v_mfma_f32_16x16x32_bf16 v[8:11], v[112:115], v[116:119], v[8:11]
	v_mfma_f32_16x16x32_bf16 v[12:15], v[120:123], v[124:127], v[12:15]
	v_mfma_f32_16x16x32_bf16 v[8:11], v[128:131], v[132:135], v[8:11]
	v_mfma_f32_16x16x32_bf16 v[12:15], v[136:139], v[140:143], v[12:15]
	global_load_dwordx4 v[80:83], v4, s[92:93] offset:2560
	global_load_dwordx4 v[84:87], v6, s[94:95] offset:2560
	global_load_dwordx4 v[88:91], v4, s[92:93] offset:2624
	global_load_dwordx4 v[92:95], v6, s[94:95] offset:2624
	global_load_dwordx4 v[96:99], v4, s[92:93] offset:2688
	global_load_dwordx4 v[100:103], v6, s[94:95] offset:2688
	global_load_dwordx4 v[104:107], v4, s[92:93] offset:2752
	global_load_dwordx4 v[108:111], v6, s[94:95] offset:2752
	global_load_dwordx4 v[112:115], v4, s[92:93] offset:2816
	global_load_dwordx4 v[116:119], v6, s[94:95] offset:2816
	global_load_dwordx4 v[120:123], v4, s[92:93] offset:2880
	global_load_dwordx4 v[124:127], v6, s[94:95] offset:2880
	global_load_dwordx4 v[128:131], v4, s[92:93] offset:2944
	global_load_dwordx4 v[132:135], v6, s[94:95] offset:2944
	global_load_dwordx4 v[136:139], v4, s[92:93] offset:3008
	global_load_dwordx4 v[140:143], v6, s[94:95] offset:3008
	s_waitcnt vmcnt(16)
	v_mfma_f32_16x16x32_bf16 v[8:11], v[16:19], v[20:23], v[8:11]
	v_mfma_f32_16x16x32_bf16 v[12:15], v[24:27], v[28:31], v[12:15]
	v_mfma_f32_16x16x32_bf16 v[8:11], v[32:35], v[36:39], v[8:11]
	v_mfma_f32_16x16x32_bf16 v[12:15], v[40:43], v[44:47], v[12:15]
	v_mfma_f32_16x16x32_bf16 v[8:11], v[48:51], v[52:55], v[8:11]
	v_mfma_f32_16x16x32_bf16 v[12:15], v[56:59], v[60:63], v[12:15]
	v_mfma_f32_16x16x32_bf16 v[8:11], v[64:67], v[68:71], v[8:11]
	v_mfma_f32_16x16x32_bf16 v[12:15], v[72:75], v[76:79], v[12:15]
	global_load_dwordx4 v[16:19], v4, s[92:93] offset:3072
	global_load_dwordx4 v[20:23], v6, s[94:95] offset:3072
	global_load_dwordx4 v[24:27], v4, s[92:93] offset:3136
	global_load_dwordx4 v[28:31], v6, s[94:95] offset:3136
	global_load_dwordx4 v[32:35], v4, s[92:93] offset:3200
	global_load_dwordx4 v[36:39], v6, s[94:95] offset:3200
	global_load_dwordx4 v[40:43], v4, s[92:93] offset:3264
	global_load_dwordx4 v[44:47], v6, s[94:95] offset:3264
	global_load_dwordx4 v[48:51], v4, s[92:93] offset:3328
	global_load_dwordx4 v[52:55], v6, s[94:95] offset:3328
	global_load_dwordx4 v[56:59], v4, s[92:93] offset:3392
	global_load_dwordx4 v[60:63], v6, s[94:95] offset:3392
	global_load_dwordx4 v[64:67], v4, s[92:93] offset:3456
	global_load_dwordx4 v[68:71], v6, s[94:95] offset:3456
	global_load_dwordx4 v[72:75], v4, s[92:93] offset:3520
	global_load_dwordx4 v[76:79], v6, s[94:95] offset:3520
	s_waitcnt vmcnt(16)
	v_mfma_f32_16x16x32_bf16 v[8:11], v[80:83], v[84:87], v[8:11]
	v_mfma_f32_16x16x32_bf16 v[12:15], v[88:91], v[92:95], v[12:15]
	v_mfma_f32_16x16x32_bf16 v[8:11], v[96:99], v[100:103], v[8:11]
	v_mfma_f32_16x16x32_bf16 v[12:15], v[104:107], v[108:111], v[12:15]
	v_mfma_f32_16x16x32_bf16 v[8:11], v[112:115], v[116:119], v[8:11]
	v_mfma_f32_16x16x32_bf16 v[12:15], v[120:123], v[124:127], v[12:15]
	v_mfma_f32_16x16x32_bf16 v[8:11], v[128:131], v[132:135], v[8:11]
	v_mfma_f32_16x16x32_bf16 v[12:15], v[136:139], v[140:143], v[12:15]
	global_load_dwordx4 v[80:83], v4, s[92:93] offset:3584
	global_load_dwordx4 v[84:87], v6, s[94:95] offset:3584
	global_load_dwordx4 v[88:91], v4, s[92:93] offset:3648
	global_load_dwordx4 v[92:95], v6, s[94:95] offset:3648
	global_load_dwordx4 v[96:99], v4, s[92:93] offset:3712
	global_load_dwordx4 v[100:103], v6, s[94:95] offset:3712
	global_load_dwordx4 v[104:107], v4, s[92:93] offset:3776
	global_load_dwordx4 v[108:111], v6, s[94:95] offset:3776
	global_load_dwordx4 v[112:115], v4, s[92:93] offset:3840
	global_load_dwordx4 v[116:119], v6, s[94:95] offset:3840
	global_load_dwordx4 v[120:123], v4, s[92:93] offset:3904
	global_load_dwordx4 v[124:127], v6, s[94:95] offset:3904
	global_load_dwordx4 v[128:131], v4, s[92:93] offset:3968
	global_load_dwordx4 v[132:135], v6, s[94:95] offset:3968
	global_load_dwordx4 v[136:139], v4, s[92:93] offset:4032
	global_load_dwordx4 v[140:143], v6, s[94:95] offset:4032
	s_waitcnt vmcnt(16)
; __device__ __forceinline__ u32x2 pk4(const f32x4 v) { return (u32x2){pk_bf16(v[0], v[1]), pk_bf16(v[2], v[3])}; }
; __device__ __forceinline__ void st8_bf16(bf16_t* p, const f32x4 a, const f32x4 b) { __builtin_nontemporal_store((u32x4){pk_bf16(a[0], a[1]), pk_bf16(a[2], a[3]), pk_bf16(b[0], b[1]), pk_bf16(b[2], b[3])}, (u32x4*)p); }
;     __device__ __forceinline__ void store8(int row, int col, const f32x4 v, const f32x4 w) const { store4(row, col, v); store4(row, col + 4, w); }
;     __device__ __forceinline__ void store4(int row, int col, const f32x4 v) const { __builtin_nontemporal_store(pk4(v), (u32x2*)((bf16_t*)((unsigned char*)out + T_D0) + (size_t)row * DM + col)); }
;     __device__ __forceinline__ void store8(int row, int col, const f32x4 v, const f32x4 w) const { st8_bf16((bf16_t*)((unsigned char*)out + T_D0) + (size_t)row * DM + col, v, w); }
;     __host__ __device__ __forceinline__ bool next(int i, Unit& u) const {
;         const long L = (long)i * G + c; if (L >= nwg) return false;
;         int wgid = (int)L; { const int q = nwg / NXCD, r = nwg % NXCD, xcd = wgid % NXCD, off = wgid / NXCD; wgid = (xcd < r ? xcd * (q + 1) : r * (q + 1) + (xcd - r) * q) + off; }
;         const int nig = WGM * nN, gid = wgid / nig, fm = gid * WGM, gsz = (nM - fm) < WGM ? (nM - fm) : WGM;
;         u.pm = fm + ((wgid % nig) % gsz); u.pn = (wgid % nig) / gsz; return true;
	v_mfma_f32_16x16x32_bf16 v[8:11], v[16:19], v[20:23], v[8:11]
	v_mfma_f32_16x16x32_bf16 v[12:15], v[24:27], v[28:31], v[12:15]
	v_mfma_f32_16x16x32_bf16 v[8:11], v[32:35], v[36:39], v[8:11]
	v_mfma_f32_16x16x32_bf16 v[12:15], v[40:43], v[44:47], v[12:15]
	v_mfma_f32_16x16x32_bf16 v[8:11], v[48:51], v[52:55], v[8:11]
	v_mfma_f32_16x16x32_bf16 v[12:15], v[56:59], v[60:63], v[12:15]
	v_mfma_f32_16x16x32_bf16 v[8:11], v[64:67], v[68:71], v[8:11]
	v_mfma_f32_16x16x32_bf16 v[12:15], v[72:75], v[76:79], v[12:15]
	s_waitcnt vmcnt(0)
	v_mfma_f32_16x16x32_bf16 v[8:11], v[80:83], v[84:87], v[8:11]
	v_mfma_f32_16x16x32_bf16 v[12:15], v[88:91], v[92:95], v[12:15]
	v_mfma_f32_16x16x32_bf16 v[8:11], v[96:99], v[100:103], v[8:11]
	v_mfma_f32_16x16x32_bf16 v[12:15], v[104:107], v[108:111], v[12:15]
	v_mfma_f32_16x16x32_bf16 v[8:11], v[112:115], v[116:119], v[8:11]
	v_mfma_f32_16x16x32_bf16 v[12:15], v[120:123], v[124:127], v[12:15]
	v_mfma_f32_16x16x32_bf16 v[8:11], v[128:131], v[132:135], v[8:11]
	v_mfma_f32_16x16x32_bf16 v[12:15], v[136:139], v[140:143], v[12:15]
	s_nop 7
	s_nop 3
	v_pk_add_f32 v[8:9], v[8:9], v[12:13]
	v_pk_add_f32 v[10:11], v[10:11], v[14:15]
	v_lshlrev_b32_e32 v7, 4, v2
	v_lshl_add_u32 v7, v1, 2, v7
	v_lshlrev_b32_e32 v16, 11, v5
	v_lshl_add_u32 v16, v7, 1, v16
	s_lshl_b32 s90, s88, 16
	s_lshl_b32 s91, s89, 7
	s_add_u32 s96, s84, 0x8100000
	s_addc_u32 s97, s85, 0
	s_add_u32 s96, s96, 0x8000000
	s_addc_u32 s97, s97, 0
	s_add_u32 s96, s96, s90
	s_addc_u32 s97, s97, 0
	s_add_u32 s96, s96, s91
	s_addc_u32 s97, s97, 0
	v_cvt_pk_bf16_f32 v18, v8, v9
	v_cvt_pk_bf16_f32 v19, v10, v11
	global_store_dwordx2 v16, v[18:19], s[96:97] nt
	s_mov_b64 s[4:5], s[0:1]
	s_load_dword s3, s[0:1], 0x118
	v_readfirstlane_b32 s14, v170
	s_waitcnt lgkmcnt(0)
	v_cvt_f32_u32_e32 v0, s3
	s_sub_i32 s8, 0, s3
	v_rcp_iflag_f32_e32 v0, v0
	s_nop 0
	v_mul_f32_e32 v0, 0x4f7ffffe, v0
	v_cvt_u32_f32_e32 v0, v0
	s_nop 0
	v_readfirstlane_b32 s9, v0
	s_mul_i32 s8, s8, s9
	s_mul_hi_u32 s8, s9, s8
	s_add_i32 s9, s9, s8
	s_mul_hi_u32 s8, s2, s9
	s_mul_i32 s8, s8, s3
	s_sub_i32 s8, s2, s8
	s_sub_i32 s9, s8, s3
	s_cmp_ge_u32 s8, s3
	s_cselect_b32 s8, s9, s8
	s_sub_i32 s9, s8, s3
	s_cmp_ge_u32 s8, s3
	s_cselect_b32 s33, s9, s8
	s_cmpk_gt_i32 s33, 0x3ff
	s_cbranch_scc1 .LBB0_689
	s_load_dwordx4 s[8:11], s[4:5], 0x100
	v_lshrrev_b32_e32 v0, 5, v170
	v_lshrrev_b32_e32 v2, 1, v170
	v_and_b32_e32 v0, 4, v0
	v_bfe_u32 v1, v170, 2, 2
	v_and_b32_e32 v11, 24, v2
	v_or3_b32 v0, v0, v1, v11
	v_lshlrev_b32_e32 v1, 4, v170
	v_add_u32_e32 v8, 0x2000, v1
	v_lshrrev_b32_e32 v2, 7, v8
	s_movk_i32 s4, 0xe0
	v_and_b32_e32 v4, 32, v170
	s_waitcnt lgkmcnt(0)
	s_add_u32 s42, s10, 0x58e0000
	v_and_or_b32 v3, v2, s4, v0
	v_bitop3_b32 v9, v1, v4, 48 bitop3:0x6c
	v_and_b32_e32 v10, 64, v170
	v_bfe_u32 v12, v170, 2, 4
	s_movk_i32 s4, 0xf0
	s_addc_u32 s43, s11, 0
	v_or_b32_e32 v1, v9, v10
	v_and_or_b32 v2, v2, s4, v12
	s_add_u32 s44, s10, 0x1c80000
	v_lshl_or_b32 v130, v2, 12, v1
	v_lshrrev_b32_e32 v2, 3, v170
	s_movk_i32 s4, 0x60
	s_addc_u32 s45, s11, 0
	v_and_or_b32 v0, v2, s4, v0
	s_movk_i32 s4, 0x70
	s_ashr_i32 s47, s33, 31
	v_lshl_or_b32 v132, v0, 12, v1
	v_and_or_b32 v0, v2, s4, v12
	s_lshr_b32 s4, s47, 29
	s_add_i32 s4, s33, s4
	s_lshr_b32 s12, s14, 6
	s_ashr_i32 s10, s4, 3
	s_and_b32 s4, s4, -8
	s_lshr_b32 s5, s14, 8
	s_lshl_b32 s46, s12, 10
	s_sub_i32 s4, s33, s4
	s_cmp_lt_i32 s4, 0
	s_movk_i32 s50, 0x81
	s_cselect_b32 s11, s50, 0x80
	s_mul_i32 s4, s11, s4
	s_add_i32 s4, s4, s10
	s_ashr_i32 s10, s4, 31
	s_lshr_b32 s10, s10, 27
	s_add_i32 s10, s4, s10
	s_ashr_i32 s11, s10, 5
	s_lshl_b32 s13, s11, 3
	s_sub_i32 s11, 0x100, s13
	s_min_u32 s15, s11, 8
	s_andn2_b32 s10, s10, 31
	v_lshl_or_b32 v128, v3, 12, v1
	s_sub_i32 s16, s4, s10
	v_cvt_f32_ubyte0_e32 v3, s15
	v_cvt_f32_i32_e32 v2, s16
	v_rcp_iflag_f32_e32 v4, v3
	v_lshl_or_b32 v134, v0, 12, v1
	s_ashr_i32 s4, s16, 30
	s_or_b32 s4, s4, 1
	v_mul_f32_e32 v0, v2, v4
	v_trunc_f32_e32 v0, v0
	v_fma_f32 v1, -v0, v3, v2
	v_cvt_i32_f32_e32 v0, v0
	v_cmp_ge_f32_e64 s[10:11], |v1|, v3
	s_and_b64 s[10:11], s[10:11], exec
	s_cselect_b32 s4, s4, 0
	v_readfirstlane_b32 s10, v0
	s_add_i32 s4, s10, s4
	s_mul_i32 s10, s4, s15
	s_sub_i32 s10, s16, s10
	s_sext_i32_i8 s10, s10
	s_add_i32 s24, s13, s10
	s_ashr_i32 s25, s24, 31
	s_bfe_i64 s[16:17], s[4:5], 0x80000
	s_lshl_b64 s[10:11], s[24:25], 20
	s_lshl_b64 s[16:17], s[16:17], 20
	s_add_u32 s38, s44, s16
	s_addc_u32 s39, s45, s17
	s_add_i32 s25, s46, 0
	s_add_i32 m0, s25, 0x10000
	v_mov_b32_e32 v133, 0
	global_load_lds_dwordx4 v132, s[38:39]
	s_add_i32 m0, s25, 0x12000
	s_add_u32 s16, s38, 0x80000
	global_load_lds_dwordx4 v128, s[38:39]
	s_addc_u32 s17, s39, 0
	s_add_i32 m0, s25, 0x14000
	v_mov_b32_e32 v129, v133
	global_load_lds_dwordx4 v132, s[16:17]
	s_add_i32 m0, s25, 0x16000
	s_add_u32 s36, s42, s10
	s_addc_u32 s37, s43, s11
	s_add_i32 s51, s25, 0x2000
	global_load_lds_dwordx4 v128, s[16:17]
	s_mov_b32 m0, s25
	s_add_u32 s10, s36, 0x80000
	global_load_lds_dwordx4 v134, s[36:37]
	s_mov_b32 m0, s51
	s_addc_u32 s11, s37, 0
	s_add_i32 s52, s25, 0x4000
	global_load_lds_dwordx4 v130, s[36:37]
	s_mov_b32 m0, s52
	s_add_i32 s53, s25, 0x6000
	global_load_lds_dwordx4 v134, s[10:11]
	s_mov_b32 m0, s53
	v_mov_b32_e32 v135, v133
	global_load_lds_dwordx4 v130, s[10:11]
	v_mov_b32_e32 v131, v133
	s_cmp_eq_u32 s5, 1
	v_lshl_add_u64 v[6:7], s[38:39], 0, v[132:133]
	v_lshl_add_u64 v[4:5], s[38:39], 0, v[128:129]
	v_lshl_add_u64 v[0:1], s[36:37], 0, v[134:135]
	s_cselect_b64 s[10:11], -1, 0
	s_cmp_lg_u32 s5, 1
	v_lshl_add_u64 v[2:3], s[36:37], 0, v[130:131]
	s_cbranch_scc1 .LBB0_676
	s_barrier
; #define PG8_STAGE(bufoff, gbase, voff) do { _Pragma("unroll") for (int _i = 0; _i < 2; ++_i) \
;         __builtin_amdgcn_global_load_lds((const unsigned*)((const char*)(gbase) + (voff)[_i]), (PG8_LAS unsigned*)(lds + (bufoff) + ldsw + _i * 8192), 16, 0, 0); } while (0)
; #define PG8_WAIT_V(n) asm volatile("s_waitcnt vmcnt(" #n ")" ::: "memory")
; #define PG8_BAR __builtin_amdgcn_s_barrier()
; template <class Epi, class Sched, bool ALIGN_EPI = false, bool SP2 = false>
; __device__ __forceinline__ void gemm_phase(PG8_LAS unsigned char* lds, const Gemm g, const Sched& S, const Epi& E) {
;     ...
;     for (int i = 0; i < 2; ++i) { int R, C; stage_rc(tid * 16 + i * 8192, R, C); const int Rb = Epi::PERM ? ((R & ~31) + perm32(R & 31)) : R;
;         voffA[i] = (unsigned)(R * K + C) * 2u; voffB[i] = (unsigned)(Rb * K + C) * 2u; }
;     const size_t kstep = (size_t)(BK * 2);
;     const size_t hstep = (size_t)HALF * K * 2;
;     const size_t tstep = 2 * hstep;
;     const unsigned ldsw = (unsigned)wid * 1024u;
;     const int aoff = lds_byte(wr * 64 + fr, fq * 8), boff = lds_byte(wc * 32 + fr, fq * 8);
;     ...
;         PG8_WAIT_V(2); PG8_BAR;
;         PG8_STAGE(PG8_SB(1, 0), cB + kstep, voffB); PG8_STAGE(PG8_SA(1, 0), cA + kstep, voffA); PG8_STAGE(PG8_SB(1, 1), cB + hstep + kstep, voffB);
;         PG8_WAIT_V(6); PG8_BAR;
;     } else {
;         PG8_STAGE(PG8_SB(0, 0), cB, voffB); PG8_STAGE(PG8_SA(0, 0), cA, voffA); PG8_STAGE(PG8_SB(0, 1), cB + hstep, voffB); PG8_STAGE(PG8_SA(0, 1), cA + hstep, voffA);
;         if (wr == 1) PG8_BAR;
;         PG8_WAIT_V(4); PG8_BAR;
;         PG8_STAGE(PG8_SB(1, 0), cB + kstep, voffB); PG8_STAGE(PG8_SA(1, 0), cA + kstep, voffA); PG8_STAGE(PG8_SB(1, 1), cB + hstep + kstep, voffB);
;         PG8_WAIT_V(6); PG8_BAR;
.LBB0_676:
	s_lshl_b32 s12, s12, 5
	s_and_b32 s18, s12, 0x60
	s_mov_b64 s[12:13], 0x80
	s_add_i32 m0, s25, 0x18000
	v_lshl_add_u64 v[6:7], v[6:7], 0, s[12:13]
	s_lshl_b32 s15, s5, 13
	s_lshl_b32 s19, s18, 7
	s_waitcnt vmcnt(2)
	s_barrier
	global_load_lds_dwordx4 v[6:7], off
	v_lshl_add_u64 v[4:5], v[4:5], 0, s[12:13]
	s_add_i32 m0, s25, 0x1a000
	s_add_i32 s54, s25, 0x8000
	s_add_i32 s55, s25, 0xa000
	global_load_lds_dwordx4 v[4:5], off
	v_lshl_add_u64 v[0:1], v[0:1], 0, s[12:13]
	s_mov_b32 m0, s54
	s_add_u32 s16, s38, 0x80080
	global_load_lds_dwordx4 v[0:1], off
	v_lshl_add_u64 v[0:1], v[2:3], 0, s[12:13]
	s_mov_b32 m0, s55
	s_addc_u32 s17, s39, 0
	global_load_lds_dwordx4 v[0:1], off
	s_add_i32 m0, s25, 0x1c000
	v_lshl_add_u64 v[0:1], s[16:17], 0, v[132:133]
	global_load_lds_dwordx4 v[0:1], off
	v_lshl_add_u64 v[0:1], s[16:17], 0, v[128:129]
	s_add_i32 m0, s25, 0x1e000
	s_sext_i32_i8 s64, s4
	global_load_lds_dwordx4 v[0:1], off
	v_and_b32_e32 v0, 15, v170
	v_lshlrev_b32_e32 v1, 1, v11
	v_lshlrev_b32_e32 v2, 2, v170
	v_lshlrev_b32_e32 v3, 6, v170
	s_movk_i32 s4, 0x3c0
	v_lshl_or_b32 v144, s5, 6, v0
	v_lshl_or_b32 v0, v0, 6, v1
	v_and_b32_e32 v2, 32, v2
	v_and_or_b32 v1, v3, s4, v1
	v_bitop3_b32 v145, s19, v1, v2 bitop3:0xf6
	v_lshlrev_b32_e32 v1, 9, v170
	v_bitop3_b32 v0, v0, s15, v2 bitop3:0xde
	v_and_b32_e32 v1, 0x70000, v1
	v_lshlrev_b32_e32 v2, 12, v12
	v_or3_b32 v1, v9, v1, v2
	v_add_u32_e32 v136, v1, v10
	v_lshlrev_b32_e32 v1, 5, v8
	s_waitcnt vmcnt(6)
	s_cmpk_lt_u32 s14, 0x100
	v_and_b32_e32 v1, 0xf0000, v1
	s_cselect_b64 s[14:15], -1, 0
	v_or3_b32 v1, v9, v1, v2
	s_add_i32 s58, 0, 0x10000
	s_add_i32 s59, 0, 0x14000
	s_mov_b32 s56, 0
	s_ashr_i32 s57, s3, 31
	v_or_b32_e32 v146, s18, v11
	v_mov_b32_e32 v137, v133
	v_add_u32_e32 v138, v1, v10
	v_mov_b32_e32 v139, v133
	v_mov_b64_e32 v[140:141], 0x400
	v_mov_b64_e32 v[142:143], 0x3ff
	v_add_u32_e32 v147, s58, v145
	v_add_u32_e32 v148, s59, v145
	v_add_u32_e32 v149, 0, v0
	s_mov_b64 s[16:17], 0x40000
	s_mov_b32 s60, 0x40000
	s_mov_b64 s[18:19], 0x48000
	s_mov_b32 s61, 0x48000
	s_mov_b64 s[20:21], 0x50000
	s_mov_b32 s62, 0x50000
	s_mov_b64 s[22:23], 0x58000
	s_mov_b32 s63, 0x58000
	s_barrier
	s_branch .LBB0_679

;     __host__ __device__ __forceinline__ bool next(int i, Unit& u) const {
;         const long L = (long)i * G + c; if (L >= nwg) return false;
;         int wgid = (int)L; { const int q = nwg / NXCD, r = nwg % NXCD, xcd = wgid % NXCD, off = wgid / NXCD; wgid = (xcd < r ? xcd * (q + 1) : r * (q + 1) + (xcd - r) * q) + off; }
;         const int nig = WGM * nN, gid = wgid / nig, fm = gid * WGM, gsz = (nM - fm) < WGM ? (nM - fm) : WGM;
;         u.pm = fm + ((wgid % nig) % gsz); u.pn = (wgid % nig) / gsz; return true;
; template <class Epi, class Sched, bool ALIGN_EPI = false, bool SP2 = false>
; __device__ __forceinline__ void gemm_phase(PG8_LAS unsigned char* lds, const Gemm g, const Sched& S, const Epi& E) {
;     ...
;         const bool has_next = S.next(ui + 1, nxt);
;         const char* nA = has_next ? (const char*)g.A + (size_t)nxt.pm * tstep : cA; const char* nB = has_next ? (const char*)g.Bt + (size_t)nxt.pn * tstep : cB;
.LBB0_679:
	s_add_i32 s56, s56, 1
	s_mul_i32 s4, s56, s57
	s_mul_hi_u32 s5, s56, s3
	s_add_i32 s5, s5, s4
	s_mul_i32 s4, s56, s3
	s_add_u32 s30, s4, s33
	s_addc_u32 s31, s5, s47
	v_cmp_gt_i64_e32 vcc, s[30:31], v[142:143]
	v_cmp_lt_i64_e64 s[4:5], s[30:31], v[140:141]
	s_cbranch_vccnz .LBB0_681
	s_ashr_i32 s26, s30, 31
	s_lshr_b32 s26, s26, 29
	s_add_i32 s26, s30, s26
	s_ashr_i32 s27, s26, 3
	s_and_b32 s26, s26, -8
	s_sub_i32 s26, s30, s26
	s_cmp_lt_i32 s26, 0
	s_cselect_b32 s28, s50, 0x80
	s_mul_i32 s26, s28, s26
	s_add_i32 s26, s26, s27
	s_ashr_i32 s27, s26, 31
	s_lshr_b32 s27, s27, 27
	s_add_i32 s27, s26, s27
	s_ashr_i32 s28, s27, 5
	s_lshl_b32 s28, s28, 3
	s_sub_i32 s29, 0x100, s28
	s_min_i32 s29, s29, 8
	s_abs_i32 s30, s29
	v_cvt_f32_u32_e32 v0, s30
	s_sub_i32 s34, 0, s30
	s_andn2_b32 s27, s27, 31
	s_sub_i32 s27, s26, s27
	v_rcp_iflag_f32_e32 v0, v0
	s_abs_i32 s26, s27
	s_xor_b32 s31, s27, s29
	s_ashr_i32 s31, s31, 31
	v_mul_f32_e32 v0, 0x4f7ffffe, v0
	v_cvt_u32_f32_e32 v0, v0
	s_nop 0
	v_readfirstlane_b32 s35, v0
	s_mul_i32 s34, s34, s35
	s_mul_hi_u32 s34, s35, s34
	s_add_i32 s35, s35, s34
	s_mul_hi_u32 s34, s26, s35
	s_mul_i32 s35, s34, s30
	s_sub_i32 s26, s26, s35
	s_add_i32 s40, s34, 1
	s_sub_i32 s35, s26, s30
	s_cmp_ge_u32 s26, s30
	s_cselect_b32 s34, s40, s34
	s_cselect_b32 s26, s35, s26
	s_add_i32 s35, s34, 1
	s_cmp_ge_u32 s26, s30
	s_cselect_b32 s26, s35, s34
	s_xor_b32 s26, s26, s31
	s_sub_i32 s26, s26, s31
	s_mul_i32 s29, s26, s29
	s_sub_i32 s27, s27, s29
	s_add_i32 s28, s27, s28

;     __device__ __forceinline__ void store4(int row, int col, const f32x4 v) const { __builtin_nontemporal_store(pk4(v), (u32x2*)((bf16_t*)((unsigned char*)out + T_D0) + (size_t)row * DM + col)); }
; #define PH(n) if ((n) > a.ph_lo && (n) < a.ph_hi) cg::this_grid().sync(); if ((n) >= a.ph_lo && (n) < a.ph_hi)
;     __device__ __forceinline__ void store4(int row, int col, const f32x4 v) const {
;         const f32x4 x = row < MP ? *(const f32x4*)(xp + (size_t)row * DM + col) : *(const f32x4*)(xs + (size_t)(row - MP) * DM + col);
; __global__ void __launch_bounds__(NTHR) mega(Args a) {
;     ...
;     PH(9) { const Args A = load_args(); unsigned char* ws = A.ws; unsigned char* ob = (unsigned char*)A.out; (void)ws; (void)ob; EpiOut1 E{A.in[0], A.in[2], A.out, ws};
;             gemm_pg8(lds, (const bf16_t*)(ws + WS_BRANCH), (const bf16_t*)(ws + WS_WOUT_T) + (size_t)1024 * 2048, MT, 1024, 2048, E); }
.LBB0_1219:
	s_cmp_lt_i32 s48, 10
	s_cselect_b64 s[10:11], -1, 0
	s_and_b64 s[4:5], s[10:11], s[4:5]
	s_andn2_b64 vcc, exec, s[4:5]
	s_cbranch_vccnz .LBB0_1366
	s_load_dwordx4 s[84:87], s[0:1], 0x100
	s_load_dwordx2 s[98:99], s[0:1], 0x10
	v_and_b32_e32 v0, 15, v170
	v_bfe_u32 v1, v170, 4, 2
	v_bfe_u32 v2, v170, 6, 2
	v_lshrrev_b32_e32 v3, 8, v170
	v_lshl_add_u32 v4, v2, 4, v0
	v_lshlrev_b32_e32 v4, 12, v4
	v_lshl_add_u32 v4, v1, 4, v4
	v_lshl_add_u32 v5, v3, 4, v0
	v_lshlrev_b32_e32 v6, 12, v5
	v_lshl_add_u32 v6, v1, 4, v6
	s_lshr_b32 s88, s2, 4
	s_and_b32 s89, s2, 15
	s_waitcnt lgkmcnt(0)
	s_lshl_b32 s90, s89, 18
	s_add_u32 s92, s86, 0x2080000
	s_addc_u32 s93, s87, 0
	s_add_u32 s92, s92, s90
	s_addc_u32 s93, s93, 0
	s_lshl_b32 s90, s88, 17
	s_add_u32 s94, s86, 0x58e0000
	s_addc_u32 s95, s87, 0
	s_add_u32 s94, s94, 0x10000000
	s_addc_u32 s95, s95, 0
	s_add_u32 s94, s94, s90
	s_addc_u32 s95, s95, 0
	global_load_dwordx4 v[16:19], v4, s[92:93] offset:0
	global_load_dwordx4 v[20:23], v6, s[94:95] offset:0
	global_load_dwordx4 v[24:27], v4, s[92:93] offset:64
	global_load_dwordx4 v[28:31], v6, s[94:95] offset:64
	global_load_dwordx4 v[32:35], v4, s[92:93] offset:128
	global_load_dwordx4 v[36:39], v6, s[94:95] offset:128
	global_load_dwordx4 v[40:43], v4, s[92:93] offset:192
	global_load_dwordx4 v[44:47], v6, s[94:95] offset:192
	global_load_dwordx4 v[48:51], v4, s[92:93] offset:256
	global_load_dwordx4 v[52:55], v6, s[94:95] offset:256
	global_load_dwordx4 v[56:59], v4, s[92:93] offset:320
	global_load_dwordx4 v[60:63], v6, s[94:95] offset:320
	global_load_dwordx4 v[64:67], v4, s[92:93] offset:384
	global_load_dwordx4 v[68:71], v6, s[94:95] offset:384
	global_load_dwordx4 v[72:75], v4, s[92:93] offset:448
	global_load_dwordx4 v[76:79], v6, s[94:95] offset:448
	global_load_dwordx4 v[80:83], v4, s[92:93] offset:512
	global_load_dwordx4 v[84:87], v6, s[94:95] offset:512
	global_load_dwordx4 v[88:91], v4, s[92:93] offset:576
	global_load_dwordx4 v[92:95], v6, s[94:95] offset:576
	global_load_dwordx4 v[96:99], v4, s[92:93] offset:640
	global_load_dwordx4 v[100:103], v6, s[94:95] offset:640
	global_load_dwordx4 v[104:107], v4, s[92:93] offset:704
	global_load_dwordx4 v[108:111], v6, s[94:95] offset:704
	global_load_dwordx4 v[112:115], v4, s[92:93] offset:768
	global_load_dwordx4 v[116:119], v6, s[94:95] offset:768
	global_load_dwordx4 v[120:123], v4, s[92:93] offset:832
	global_load_dwordx4 v[124:127], v6, s[94:95] offset:832
	global_load_dwordx4 v[128:131], v4, s[92:93] offset:896
	global_load_dwordx4 v[132:135], v6, s[94:95] offset:896
	global_load_dwordx4 v[136:139], v4, s[92:93] offset:960
	global_load_dwordx4 v[140:143], v6, s[94:95] offset:960
	s_waitcnt vmcnt(16)
	v_mfma_f32_16x16x32_bf16 v[8:11], v[16:19], v[20:23], 0
	v_mfma_f32_16x16x32_bf16 v[12:15], v[24:27], v[28:31], 0
	v_mfma_f32_16x16x32_bf16 v[8:11], v[32:35], v[36:39], v[8:11]
	v_mfma_f32_16x16x32_bf16 v[12:15], v[40:43], v[44:47], v[12:15]
	v_mfma_f32_16x16x32_bf16 v[8:11], v[48:51], v[52:55], v[8:11]
	v_mfma_f32_16x16x32_bf16 v[12:15], v[56:59], v[60:63], v[12:15]
	v_mfma_f32_16x16x32_bf16 v[8:11], v[64:67], v[68:71], v[8:11]
	v_mfma_f32_16x16x32_bf16 v[12:15], v[72:75], v[76:79], v[12:15]
	global_load_dwordx4 v[16:19], v4, s[92:93] offset:1024
	global_load_dwordx4 v[20:23], v6, s[94:95] offset:1024
	global_load_dwordx4 v[24:27], v4, s[92:93] offset:1088
	global_load_dwordx4 v[28:31], v6, s[94:95] offset:1088
	global_load_dwordx4 v[32:35], v4, s[92:93] offset:1152
	global_load_dwordx4 v[36:39], v6, s[94:95] offset:1152
	global_load_dwordx4 v[40:43], v4, s[92:93] offset:1216
	global_load_dwordx4 v[44:47], v6, s[94:95] offset:1216
	global_load_dwordx4 v[48:51], v4, s[92:93] offset:1280
	global_load_dwordx4 v[52:55], v6, s[94:95] offset:1280
	global_load_dwordx4 v[56:59], v4, s[92:93] offset:1344
	global_load_dwordx4 v[60:63], v6, s[94:95] offset:1344
	global_load_dwordx4 v[64:67], v4, s[92:93] offset:1408
	global_load_dwordx4 v[68:71], v6, s[94:95] offset:1408
	global_load_dwordx4 v[72:75], v4, s[92:93] offset:1472
	global_load_dwordx4 v[76:79], v6, s[94:95] offset:1472
	s_waitcnt vmcnt(16)
	v_mfma_f32_16x16x32_bf16 v[8:11], v[80:83], v[84:87], v[8:11]
	v_mfma_f32_16x16x32_bf16 v[12:15], v[88:91], v[92:95], v[12:15]
	v_mfma_f32_16x16x32_bf16 v[8:11], v[96:99], v[100:103], v[8:11]
	v_mfma_f32_16x16x32_bf16 v[12:15], v[104:107], v[108:111], v[12:15]
	v_mfma_f32_16x16x32_bf16 v[8:11], v[112:115], v[116:119], v[8:11]
	v_mfma_f32_16x16x32_bf16 v[12:15], v[120:123], v[124:127], v[12:15]
	v_mfma_f32_16x16x32_bf16 v[8:11], v[128:131], v[132:135], v[8:11]
	v_mfma_f32_16x16x32_bf16 v[12:15], v[136:139], v[140:143], v[12:15]
	global_load_dwordx4 v[80:83], v4, s[92:93] offset:1536
	global_load_dwordx4 v[84:87], v6, s[94:95] offset:1536
	global_load_dwordx4 v[88:91], v4, s[92:93] offset:1600
	global_load_dwordx4 v[92:95], v6, s[94:95] offset:1600
	global_load_dwordx4 v[96:99], v4, s[92:93] offset:1664
	global_load_dwordx4 v[100:103], v6, s[94:95] offset:1664
	global_load_dwordx4 v[104:107], v4, s[92:93] offset:1728
	global_load_dwordx4 v[108:111], v6, s[94:95] offset:1728
	global_load_dwordx4 v[112:115], v4, s[92:93] offset:1792
	global_load_dwordx4 v[116:119], v6, s[94:95] offset:1792
	global_load_dwordx4 v[120:123], v4, s[92:93] offset:1856
	global_load_dwordx4 v[124:127], v6, s[94:95] offset:1856
	global_load_dwordx4 v[128:131], v4, s[92:93] offset:1920
	global_load_dwordx4 v[132:135], v6, s[94:95] offset:1920
	global_load_dwordx4 v[136:139], v4, s[92:93] offset:1984
	global_load_dwordx4 v[140:143], v6, s[94:95] offset:1984
	s_waitcnt vmcnt(16)
; #define PH(n) if ((n) > a.ph_lo && (n) < a.ph_hi) cg::this_grid().sync(); if ((n) >= a.ph_lo && (n) < a.ph_hi)
; __global__ void __launch_bounds__(NTHR) mega(Args a) {
;     ...
;     PH(9) { const Args A = load_args(); unsigned char* ws = A.ws; unsigned char* ob = (unsigned char*)A.out; (void)ws; (void)ob; EpiOut1 E{A.in[0], A.in[2], A.out, ws};
;             gemm_pg8(lds, (const bf16_t*)(ws + WS_BRANCH), (const bf16_t*)(ws + WS_WOUT_T) + (size_t)1024 * 2048, MT, 1024, 2048, E); }
	v_mfma_f32_16x16x32_bf16 v[8:11], v[16:19], v[20:23], v[8:11]
	v_mfma_f32_16x16x32_bf16 v[12:15], v[24:27], v[28:31], v[12:15]
	v_mfma_f32_16x16x32_bf16 v[8:11], v[32:35], v[36:39], v[8:11]
	v_mfma_f32_16x16x32_bf16 v[12:15], v[40:43], v[44:47], v[12:15]
	v_mfma_f32_16x16x32_bf16 v[8:11], v[48:51], v[52:55], v[8:11]
	v_mfma_f32_16x16x32_bf16 v[12:15], v[56:59], v[60:63], v[12:15]
	v_mfma_f32_16x16x32_bf16 v[8:11], v[64:67], v[68:71], v[8:11]
	v_mfma_f32_16x16x32_bf16 v[12:15], v[72:75], v[76:79], v[12:15]
	global_load_dwordx4 v[16:19], v4, s[92:93] offset:2048
	global_load_dwordx4 v[20:23], v6, s[94:95] offset:2048
	global_load_dwordx4 v[24:27], v4, s[92:93] offset:2112
	global_load_dwordx4 v[28:31], v6, s[94:95] offset:2112
	global_load_dwordx4 v[32:35], v4, s[92:93] offset:2176
	global_load_dwordx4 v[36:39], v6, s[94:95] offset:2176
	global_load_dwordx4 v[40:43], v4, s[92:93] offset:2240
	global_load_dwordx4 v[44:47], v6, s[94:95] offset:2240
	global_load_dwordx4 v[48:51], v4, s[92:93] offset:2304
	global_load_dwordx4 v[52:55], v6, s[94:95] offset:2304
	global_load_dwordx4 v[56:59], v4, s[92:93] offset:2368
	global_load_dwordx4 v[60:63], v6, s[94:95] offset:2368
	global_load_dwordx4 v[64:67], v4, s[92:93] offset:2432
	global_load_dwordx4 v[68:71], v6, s[94:95] offset:2432
	global_load_dwordx4 v[72:75], v4, s[92:93] offset:2496
	global_load_dwordx4 v[76:79], v6, s[94:95] offset:2496
	s_waitcnt vmcnt(16)
	v_mfma_f32_16x16x32_bf16 v[8:11], v[80:83], v[84:87], v[8:11]
	v_mfma_f32_16x16x32_bf16 v[12:15], v[88:91], v[92:95], v[12:15]
	v_mfma_f32_16x16x32_bf16 v[8:11], v[96:99], v[100:103], v[8:11]
	v_mfma_f32_16x16x32_bf16 v[12:15], v[104:107], v[108:111], v[12:15]
	v_mfma_f32_16x16x32_bf16 v[8:11], v[112:115], v[116:119], v[8:11]
	v_mfma_f32_16x16x32_bf16 v[12:15], v[120:123], v[124:127], v[12:15]
	v_mfma_f32_16x16x32_bf16 v[8:11], v[128:131], v[132:135], v[8:11]
	v_mfma_f32_16x16x32_bf16 v[12:15], v[136:139], v[140:143], v[12:15]
	global_load_dwordx4 v[80:83], v4, s[92:93] offset:2560
	global_load_dwordx4 v[84:87], v6, s[94:95] offset:2560
	global_load_dwordx4 v[88:91], v4, s[92:93] offset:2624
	global_load_dwordx4 v[92:95], v6, s[94:95] offset:2624
	global_load_dwordx4 v[96:99], v4, s[92:93] offset:2688
	global_load_dwordx4 v[100:103], v6, s[94:95] offset:2688
	global_load_dwordx4 v[104:107], v4, s[92:93] offset:2752
	global_load_dwordx4 v[108:111], v6, s[94:95] offset:2752
	global_load_dwordx4 v[112:115], v4, s[92:93] offset:2816
	global_load_dwordx4 v[116:119], v6, s[94:95] offset:2816
	global_load_dwordx4 v[120:123], v4, s[92:93] offset:2880
	global_load_dwordx4 v[124:127], v6, s[94:95] offset:2880
	global_load_dwordx4 v[128:131], v4, s[92:93] offset:2944
	global_load_dwordx4 v[132:135], v6, s[94:95] offset:2944
	global_load_dwordx4 v[136:139], v4, s[92:93] offset:3008
	global_load_dwordx4 v[140:143], v6, s[94:95] offset:3008
	s_waitcnt vmcnt(16)
	v_mfma_f32_16x16x32_bf16 v[8:11], v[16:19], v[20:23], v[8:11]
	v_mfma_f32_16x16x32_bf16 v[12:15], v[24:27], v[28:31], v[12:15]
	v_mfma_f32_16x16x32_bf16 v[8:11], v[32:35], v[36:39], v[8:11]
	v_mfma_f32_16x16x32_bf16 v[12:15], v[40:43], v[44:47], v[12:15]
	v_mfma_f32_16x16x32_bf16 v[8:11], v[48:51], v[52:55], v[8:11]
	v_mfma_f32_16x16x32_bf16 v[12:15], v[56:59], v[60:63], v[12:15]
	v_mfma_f32_16x16x32_bf16 v[8:11], v[64:67], v[68:71], v[8:11]
	v_mfma_f32_16x16x32_bf16 v[12:15], v[72:75], v[76:79], v[12:15]
	global_load_dwordx4 v[16:19], v4, s[92:93] offset:3072
	global_load_dwordx4 v[20:23], v6, s[94:95] offset:3072
	global_load_dwordx4 v[24:27], v4, s[92:93] offset:3136
	global_load_dwordx4 v[28:31], v6, s[94:95] offset:3136
	global_load_dwordx4 v[32:35], v4, s[92:93] offset:3200
	global_load_dwordx4 v[36:39], v6, s[94:95] offset:3200
	global_load_dwordx4 v[40:43], v4, s[92:93] offset:3264
	global_load_dwordx4 v[44:47], v6, s[94:95] offset:3264
	global_load_dwordx4 v[48:51], v4, s[92:93] offset:3328
	global_load_dwordx4 v[52:55], v6, s[94:95] offset:3328
	global_load_dwordx4 v[56:59], v4, s[92:93] offset:3392
	global_load_dwordx4 v[60:63], v6, s[94:95] offset:3392
	global_load_dwordx4 v[64:67], v4, s[92:93] offset:3456
	global_load_dwordx4 v[68:71], v6, s[94:95] offset:3456
	global_load_dwordx4 v[72:75], v4, s[92:93] offset:3520
	global_load_dwordx4 v[76:79], v6, s[94:95] offset:3520
	s_waitcnt vmcnt(16)
; __device__ __forceinline__ float bflo(unsigned w) { return __uint_as_float(w << 16); }
; __device__ __forceinline__ float bfhi(unsigned w) { return __uint_as_float(w & 0xffff0000u); }
;     __device__ __forceinline__ void store4(int row, int col, const f32x4 v) const { __builtin_nontemporal_store(pk4(v), (u32x2*)((bf16_t*)((unsigned char*)out + T_D0) + (size_t)row * DM + col)); }
;     __device__ __forceinline__ void store8(int row, int col, const f32x4 v, const f32x4 w) const { st8_bf16((bf16_t*)((unsigned char*)out + T_D0) + (size_t)row * DM + col, v, w); }
;     __device__ __forceinline__ void store4(int row, int col, const f32x4 v) const {
;         const f32x4 x = row < MP ? *(const f32x4*)(xp + (size_t)row * DM + col) : *(const f32x4*)(xs + (size_t)(row - MP) * DM + col);
;         const u32x2 d = *(const u32x2*)((const bf16_t*)((const unsigned char*)out + T_D0) + (size_t)row * DM + col);
;         const f32x4 d0 = {bflo(d.x), bfhi(d.x), bflo(d.y), bfhi(d.y)};
;         __builtin_nontemporal_store(x + d0 + v, (f32x4*)((float*)(ws + WS_X2) + (size_t)row * DM + col));
;     }
;     __device__ __forceinline__ void store8(int row, int col, const f32x4 v, const f32x4 w) const { store4(row, col, v); store4(row, col + 4, w); }
;     __host__ __device__ __forceinline__ bool next(int i, Unit& u) const {
;         const long L = (long)i * G + c; if (L >= nwg) return false;
;         int wgid = (int)L; { const int q = nwg / NXCD, r = nwg % NXCD, xcd = wgid % NXCD, off = wgid / NXCD; wgid = (xcd < r ? xcd * (q + 1) : r * (q + 1) + (xcd - r) * q) + off; }
;         const int nig = WGM * nN, gid = wgid / nig, fm = gid * WGM, gsz = (nM - fm) < WGM ? (nM - fm) : WGM;
;         u.pm = fm + ((wgid % nig) % gsz); u.pn = (wgid % nig) / gsz; return true;
	v_mfma_f32_16x16x32_bf16 v[8:11], v[80:83], v[84:87], v[8:11]
	v_mfma_f32_16x16x32_bf16 v[12:15], v[88:91], v[92:95], v[12:15]
	v_mfma_f32_16x16x32_bf16 v[8:11], v[96:99], v[100:103], v[8:11]
	v_mfma_f32_16x16x32_bf16 v[12:15], v[104:107], v[108:111], v[12:15]
	v_mfma_f32_16x16x32_bf16 v[8:11], v[112:115], v[116:119], v[8:11]
	v_mfma_f32_16x16x32_bf16 v[12:15], v[120:123], v[124:127], v[12:15]
	v_mfma_f32_16x16x32_bf16 v[8:11], v[128:131], v[132:135], v[8:11]
	v_mfma_f32_16x16x32_bf16 v[12:15], v[136:139], v[140:143], v[12:15]
	global_load_dwordx4 v[80:83], v4, s[92:93] offset:3584
	global_load_dwordx4 v[84:87], v6, s[94:95] offset:3584
	global_load_dwordx4 v[88:91], v4, s[92:93] offset:3648
	global_load_dwordx4 v[92:95], v6, s[94:95] offset:3648
	global_load_dwordx4 v[96:99], v4, s[92:93] offset:3712
	global_load_dwordx4 v[100:103], v6, s[94:95] offset:3712
	global_load_dwordx4 v[104:107], v4, s[92:93] offset:3776
	global_load_dwordx4 v[108:111], v6, s[94:95] offset:3776
	global_load_dwordx4 v[112:115], v4, s[92:93] offset:3840
	global_load_dwordx4 v[116:119], v6, s[94:95] offset:3840
	global_load_dwordx4 v[120:123], v4, s[92:93] offset:3904
	global_load_dwordx4 v[124:127], v6, s[94:95] offset:3904
	global_load_dwordx4 v[128:131], v4, s[92:93] offset:3968
	global_load_dwordx4 v[132:135], v6, s[94:95] offset:3968
	global_load_dwordx4 v[136:139], v4, s[92:93] offset:4032
	global_load_dwordx4 v[140:143], v6, s[94:95] offset:4032
	s_waitcnt vmcnt(16)
	v_mfma_f32_16x16x32_bf16 v[8:11], v[16:19], v[20:23], v[8:11]
	v_mfma_f32_16x16x32_bf16 v[12:15], v[24:27], v[28:31], v[12:15]
	v_mfma_f32_16x16x32_bf16 v[8:11], v[32:35], v[36:39], v[8:11]
	v_mfma_f32_16x16x32_bf16 v[12:15], v[40:43], v[44:47], v[12:15]
	v_mfma_f32_16x16x32_bf16 v[8:11], v[48:51], v[52:55], v[8:11]
	v_mfma_f32_16x16x32_bf16 v[12:15], v[56:59], v[60:63], v[12:15]
	v_mfma_f32_16x16x32_bf16 v[8:11], v[64:67], v[68:71], v[8:11]
	v_mfma_f32_16x16x32_bf16 v[12:15], v[72:75], v[76:79], v[12:15]
	s_waitcnt vmcnt(0)
	v_mfma_f32_16x16x32_bf16 v[8:11], v[80:83], v[84:87], v[8:11]
	v_mfma_f32_16x16x32_bf16 v[12:15], v[88:91], v[92:95], v[12:15]
	v_mfma_f32_16x16x32_bf16 v[8:11], v[96:99], v[100:103], v[8:11]
	v_mfma_f32_16x16x32_bf16 v[12:15], v[104:107], v[108:111], v[12:15]
	v_mfma_f32_16x16x32_bf16 v[8:11], v[112:115], v[116:119], v[8:11]
	v_mfma_f32_16x16x32_bf16 v[12:15], v[120:123], v[124:127], v[12:15]
	v_mfma_f32_16x16x32_bf16 v[8:11], v[128:131], v[132:135], v[8:11]
	v_mfma_f32_16x16x32_bf16 v[12:15], v[136:139], v[140:143], v[12:15]
	s_nop 7
	s_nop 3
	v_pk_add_f32 v[8:9], v[8:9], v[12:13]
	v_pk_add_f32 v[10:11], v[10:11], v[14:15]
	v_lshlrev_b32_e32 v7, 4, v2
	v_lshl_add_u32 v7, v1, 2, v7
	v_lshlrev_b32_e32 v16, 11, v5
	v_lshl_add_u32 v16, v7, 1, v16
	s_lshl_b32 s90, s88, 16
	s_lshl_b32 s91, s89, 7
	s_add_u32 s96, s84, 0x8100000
	s_addc_u32 s97, s85, 0
	s_add_u32 s96, s96, 0x8000000
	s_addc_u32 s97, s97, 0
	s_add_u32 s96, s96, s90
	s_addc_u32 s97, s97, 0
	s_add_u32 s96, s96, s91
	s_addc_u32 s97, s97, 0
	v_lshlrev_b32_e32 v17, 12, v5
	v_lshl_add_u32 v17, v7, 2, v17
	s_lshl_b32 s90, s88, 17
	s_lshl_b32 s91, s89, 8
	s_add_u32 s98, s98, s90
	s_addc_u32 s99, s99, 0
	s_add_u32 s98, s98, s91
	s_addc_u32 s99, s99, 0
	s_add_u32 s100, s86, 0x25ce0000
	s_addc_u32 s101, s87, 0
	s_add_u32 s100, s100, 0x10000000
	s_addc_u32 s101, s101, 0
	s_add_u32 s100, s100, s90
	s_addc_u32 s101, s101, 0
	s_add_u32 s100, s100, s91
	s_addc_u32 s101, s101, 0
	global_load_dwordx4 v[20:23], v17, s[98:99]
	global_load_dwordx2 v[24:25], v16, s[96:97]
	s_waitcnt vmcnt(0)
	v_lshlrev_b32_e32 v26, 16, v24
	v_and_b32_e32 v27, 0xffff0000, v24
	v_lshlrev_b32_e32 v28, 16, v25
	v_and_b32_e32 v29, 0xffff0000, v25
	v_pk_add_f32 v[20:21], v[20:21], v[26:27]
	v_pk_add_f32 v[22:23], v[22:23], v[28:29]
	v_pk_add_f32 v[8:9], v[8:9], v[20:21]
	v_pk_add_f32 v[10:11], v[10:11], v[22:23]
	global_store_dwordx4 v17, v[8:11], s[100:101] nt
	s_waitcnt lgkmcnt(0)
	s_mov_b64 s[20:21], s[0:1]
	s_load_dword s33, s[0:1], 0x118
	v_readfirstlane_b32 s24, v170
	s_waitcnt lgkmcnt(0)
	v_cvt_f32_u32_e32 v0, s33
	s_sub_i32 s3, 0, s33
	v_rcp_iflag_f32_e32 v0, v0
	s_nop 0
	v_mul_f32_e32 v0, 0x4f7ffffe, v0
	v_cvt_u32_f32_e32 v0, v0
	s_nop 0
	v_readfirstlane_b32 s4, v0
	s_mul_i32 s3, s3, s4
	s_mul_hi_u32 s3, s4, s3
	s_add_i32 s4, s4, s3
	s_mul_hi_u32 s3, s2, s4
	s_mul_i32 s3, s3, s33
	s_sub_i32 s2, s2, s3
	s_sub_i32 s3, s2, s33
	s_cmp_ge_u32 s2, s33
	s_cselect_b32 s2, s3, s2
	s_sub_i32 s3, s2, s33
	s_cmp_ge_u32 s2, s33
	s_cselect_b32 s52, s3, s2
	s_cmpk_lt_i32 s52, 0x400
	s_cselect_b64 s[2:3], -1, 0
	s_cmpk_gt_i32 s52, 0x3ff
	s_cbranch_scc1 .LBB0_1222
	s_ashr_i32 s4, s52, 31
	s_lshr_b32 s4, s4, 29
	s_add_i32 s4, s52, s4
	s_ashr_i32 s5, s4, 3
	s_and_b32 s4, s4, -8
	s_sub_i32 s4, s52, s4
	s_cmp_lt_i32 s4, 0
	s_movk_i32 s6, 0x81
	s_cselect_b32 s6, s6, 0x80
	s_mul_i32 s4, s6, s4
	s_add_i32 s4, s4, s5
	s_ashr_i32 s5, s4, 31
	s_lshr_b32 s5, s5, 27
	s_add_i32 s5, s4, s5
	s_ashr_i32 s6, s5, 5
	s_lshl_b32 s6, s6, 3
	s_sub_i32 s7, 0x100, s6
	s_min_u32 s7, s7, 8
	s_andn2_b32 s5, s5, 31
	s_sub_i32 s8, s4, s5
	v_cvt_f32_ubyte0_e32 v1, s7
	v_cvt_f32_i32_e32 v0, s8
	v_rcp_iflag_f32_e32 v2, v1
	s_ashr_i32 s4, s8, 30
	s_or_b32 s9, s4, 1
	v_mul_f32_e32 v2, v0, v2
	v_trunc_f32_e32 v2, v2
	v_fma_f32 v0, -v2, v1, v0
	v_cvt_i32_f32_e32 v2, v2
	v_cmp_ge_f32_e64 s[4:5], |v0|, v1
	s_and_b64 s[4:5], s[4:5], exec
	s_cselect_b32 s4, s9, 0
	v_readfirstlane_b32 s5, v2
	s_add_i32 s5, s5, s4
	s_sext_i32_i8 s4, s5
	s_mul_i32 s5, s5, s7
	s_sub_i32 s5, s8, s5
	s_sext_i32_i8 s5, s5
	s_add_i32 s6, s6, s5

; #define PG8_STAGE(bufoff, gbase, voff) do { _Pragma("unroll") for (int _i = 0; _i < 2; ++_i) \
;         __builtin_amdgcn_global_load_lds((const unsigned*)((const char*)(gbase) + (voff)[_i]), (PG8_LAS unsigned*)(lds + (bufoff) + ldsw + _i * 8192), 16, 0, 0); } while (0)
; #define PG8_WAIT_V(n) asm volatile("s_waitcnt vmcnt(" #n ")" ::: "memory")
; #define PG8_BAR __builtin_amdgcn_s_barrier()
; template <class Epi, class Sched, bool ALIGN_EPI = false, bool SP2 = false>
; __device__ __forceinline__ void gemm_phase(PG8_LAS unsigned char* lds, const Gemm g, const Sched& S, const Epi& E) {
;     ...
;     for (int i = 0; i < 2; ++i) { int R, C; stage_rc(tid * 16 + i * 8192, R, C); const int Rb = Epi::PERM ? ((R & ~31) + perm32(R & 31)) : R;
;         voffA[i] = (unsigned)(R * K + C) * 2u; voffB[i] = (unsigned)(Rb * K + C) * 2u; }
;     const size_t kstep = (size_t)(BK * 2);
;     const size_t hstep = (size_t)HALF * K * 2;
;     const size_t tstep = 2 * hstep;
;     const unsigned ldsw = (unsigned)wid * 1024u;
;     const int aoff = lds_byte(wr * 64 + fr, fq * 8), boff = lds_byte(wc * 32 + fr, fq * 8);
;     ...
;         PG8_WAIT_V(2); PG8_BAR;
;         PG8_STAGE(PG8_SB(1, 0), cB + kstep, voffB); PG8_STAGE(PG8_SA(1, 0), cA + kstep, voffA); PG8_STAGE(PG8_SB(1, 1), cB + hstep + kstep, voffB);
;         PG8_WAIT_V(6); PG8_BAR;
;     } else {
;         PG8_STAGE(PG8_SB(0, 0), cB, voffB); PG8_STAGE(PG8_SA(0, 0), cA, voffA); PG8_STAGE(PG8_SB(0, 1), cB + hstep, voffB); PG8_STAGE(PG8_SA(0, 1), cA + hstep, voffA);
;         if (wr == 1) PG8_BAR;
;         PG8_WAIT_V(4); PG8_BAR;
;         PG8_STAGE(PG8_SB(1, 0), cB + kstep, voffB); PG8_STAGE(PG8_SA(1, 0), cA + kstep, voffA); PG8_STAGE(PG8_SB(1, 1), cB + hstep + kstep, voffB);
;         PG8_WAIT_V(6); PG8_BAR;
.LBB0_1225:
	s_lshl_b32 s3, s3, 5
	s_mov_b64 s[22:23], 0x80
	s_and_b32 s3, s3, 0x60
	s_add_i32 m0, s58, 0x18000
	v_lshl_add_u64 v[6:7], v[6:7], 0, s[22:23]
	s_lshl_b32 s5, s2, 13
	s_lshl_b32 s7, s3, 7
	s_waitcnt vmcnt(2)
	s_barrier
	global_load_lds_dwordx4 v[6:7], off
	v_lshl_add_u64 v[4:5], v[4:5], 0, s[22:23]
	s_add_i32 m0, s58, 0x1a000
	s_add_i32 s63, s58, 0x8000
	s_add_i32 s64, s58, 0xa000
	global_load_lds_dwordx4 v[4:5], off
	v_lshl_add_u64 v[0:1], v[0:1], 0, s[22:23]
	s_mov_b32 m0, s63
	s_add_u32 s26, s40, 0x80080
	global_load_lds_dwordx4 v[0:1], off
	v_lshl_add_u64 v[0:1], v[2:3], 0, s[22:23]
	s_mov_b32 m0, s64
	s_addc_u32 s27, s41, 0
	global_load_lds_dwordx4 v[0:1], off
	s_add_i32 m0, s58, 0x1c000
	v_lshl_add_u64 v[0:1], s[26:27], 0, v[130:131]
	global_load_lds_dwordx4 v[0:1], off
	v_lshl_add_u64 v[0:1], s[26:27], 0, v[134:135]
	s_add_i32 m0, s58, 0x1e000
	v_lshlrev_b32_e32 v2, 2, v170
	global_load_lds_dwordx4 v[0:1], off
	v_and_b32_e32 v0, 15, v170
	v_lshl_or_b32 v154, s2, 6, v0
	v_lshlrev_b32_e32 v1, 1, v11
	v_lshlrev_b32_e32 v3, 6, v170
	s_movk_i32 s2, 0x3c0
	v_lshl_or_b32 v0, v0, 6, v1
	v_and_b32_e32 v2, 32, v2
	v_and_or_b32 v1, v3, s2, v1
	v_bitop3_b32 v155, s7, v1, v2 bitop3:0xf6
	v_lshlrev_b32_e32 v1, 9, v170
	v_bitop3_b32 v0, v0, s5, v2 bitop3:0xde
	v_and_b32_e32 v1, 0x70000, v1
	v_lshlrev_b32_e32 v2, 12, v10
	v_or3_b32 v1, v8, v1, v2
	v_add_u32_e32 v138, v1, v9
	v_lshlrev_b32_e32 v1, 5, v12
	s_waitcnt vmcnt(6)
	s_cmpk_lt_u32 s24, 0x100
	v_and_b32_e32 v1, 0xf0000, v1
	s_cselect_b64 s[24:25], -1, 0
	v_or3_b32 v1, v8, v1, v2
	s_add_i32 s68, 0, 0x10000
	s_add_i32 s69, 0, 0x14000
	s_ashr_i32 s65, s33, 31
	s_ashr_i32 s66, s52, 31
	v_or_b32_e32 v156, s3, v11
	v_mov_b32_e32 v139, v137
	v_add_u32_e32 v140, v1, v9
	v_mov_b32_e32 v141, v137
	v_mov_b64_e32 v[142:143], 0x400
	v_mov_b64_e32 v[144:145], 0x3ff
	s_movk_i32 s67, 0x81
	v_add_u32_e32 v157, s68, v155
	v_add_u32_e32 v158, s69, v155
	v_add_u32_e32 v159, 0, v0
	s_mov_b32 s70, 0xffff
	s_mov_b64 s[26:27], 0x200
	s_mov_b64 s[28:29], 0x210
	s_mov_b32 s71, 0xff7f
	s_mov_b32 s72, 0xff6f
	s_mov_b32 s73, 0xff5f
	s_mov_b32 s74, 0xff4f
	s_barrier
	s_branch .LBB0_1228

;     __host__ __device__ __forceinline__ bool next(int i, Unit& u) const {
;         const long L = (long)i * G + c; if (L >= nwg) return false;
;         int wgid = (int)L; { const int q = nwg / NXCD, r = nwg % NXCD, xcd = wgid % NXCD, off = wgid / NXCD; wgid = (xcd < r ? xcd * (q + 1) : r * (q + 1) + (xcd - r) * q) + off; }
;         const int nig = WGM * nN, gid = wgid / nig, fm = gid * WGM, gsz = (nM - fm) < WGM ? (nM - fm) : WGM;
;         u.pm = fm + ((wgid % nig) % gsz); u.pn = (wgid % nig) / gsz; return true;
; template <class Epi, class Sched, bool ALIGN_EPI = false, bool SP2 = false>
; __device__ __forceinline__ void gemm_phase(PG8_LAS unsigned char* lds, const Gemm g, const Sched& S, const Epi& E) {
;     ...
;         const bool has_next = S.next(ui + 1, nxt);
;         const char* nA = has_next ? (const char*)g.A + (size_t)nxt.pm * tstep : cA; const char* nB = has_next ? (const char*)g.Bt + (size_t)nxt.pn * tstep : cB;
.LBB0_1228:
	s_add_i32 s62, s62, 1
	s_mul_i32 s2, s62, s65
	s_mul_hi_u32 s3, s62, s33
	s_add_i32 s3, s3, s2
	s_mul_i32 s2, s62, s33
	s_add_u32 s36, s2, s52
	s_addc_u32 s37, s3, s66
	v_cmp_gt_i64_e32 vcc, s[36:37], v[144:145]
	v_cmp_lt_i64_e64 s[2:3], s[36:37], v[142:143]
	s_cbranch_vccnz .LBB0_1230
	s_ashr_i32 s5, s36, 31
	s_lshr_b32 s5, s5, 29
	s_add_i32 s5, s36, s5
	s_ashr_i32 s7, s5, 3
	s_and_b32 s5, s5, -8
	s_sub_i32 s5, s36, s5
	s_cmp_lt_i32 s5, 0
	s_cselect_b32 s30, s67, 0x80
	s_mul_i32 s5, s30, s5
	s_add_i32 s5, s5, s7
	s_ashr_i32 s7, s5, 31
	s_lshr_b32 s7, s7, 27
	s_add_i32 s7, s5, s7
	s_ashr_i32 s30, s7, 5
	s_lshl_b32 s31, s30, 3
	s_sub_i32 s30, 0x100, s31
	s_min_i32 s34, s30, 8
	s_abs_i32 s30, s34
	v_cvt_f32_u32_e32 v0, s30
	s_sub_i32 s36, 0, s30
	s_andn2_b32 s7, s7, 31
	s_sub_i32 s5, s5, s7
	v_rcp_iflag_f32_e32 v0, v0
	s_abs_i32 s7, s5
	s_xor_b32 s35, s5, s34
	s_ashr_i32 s35, s35, 31
	v_mul_f32_e32 v0, 0x4f7ffffe, v0
	v_cvt_u32_f32_e32 v0, v0
	s_nop 0
	v_readfirstlane_b32 s37, v0
	s_mul_i32 s36, s36, s37
	s_mul_hi_u32 s36, s37, s36
	s_add_i32 s37, s37, s36
	s_mul_hi_u32 s36, s7, s37
	s_mul_i32 s37, s36, s30
	s_sub_i32 s7, s7, s37
	s_add_i32 s38, s36, 1
	s_sub_i32 s37, s7, s30
	s_cmp_ge_u32 s7, s30
	s_cselect_b32 s36, s38, s36
	s_cselect_b32 s7, s37, s7
	s_add_i32 s37, s36, 1
	s_cmp_ge_u32 s7, s30
	s_cselect_b32 s7, s37, s36
	s_xor_b32 s7, s7, s35
	s_sub_i32 s30, s7, s35
	s_mul_i32 s7, s30, s34
	s_sub_i32 s5, s5, s7
	s_add_i32 s34, s5, s31

; __global__ void __launch_bounds__(NTHR) mega(Args a) {
	.amdhsa_kernel _Z4mega4Args
		.amdhsa_group_segment_fixed_size 0
		.amdhsa_private_segment_fixed_size 0
		.amdhsa_kernarg_size 536
		.amdhsa_user_sgpr_count 2
		.amdhsa_user_sgpr_dispatch_ptr 0
		.amdhsa_user_sgpr_queue_ptr 0
		.amdhsa_user_sgpr_kernarg_segment_ptr 1
		.amdhsa_user_sgpr_dispatch_id 0
		.amdhsa_user_sgpr_kernarg_preload_length 0
		.amdhsa_user_sgpr_kernarg_preload_offset 0
		.amdhsa_user_sgpr_private_segment_size 0
		.amdhsa_uses_dynamic_stack 0
		.amdhsa_enable_private_segment 0
		.amdhsa_system_sgpr_workgroup_id_x 1
		.amdhsa_system_sgpr_workgroup_id_y 0
		.amdhsa_system_sgpr_workgroup_id_z 0
		.amdhsa_system_sgpr_workgroup_info 0
		.amdhsa_system_vgpr_workitem_id 2
		.amdhsa_next_free_vgpr 252
		.amdhsa_next_free_sgpr 102
		.amdhsa_accum_offset 252
		.amdhsa_reserve_vcc 1
		.amdhsa_float_round_mode_32 0
		.amdhsa_float_round_mode_16_64 0
		.amdhsa_float_denorm_mode_32 3
		.amdhsa_float_denorm_mode_16_64 3
		.amdhsa_dx10_clamp 1
		.amdhsa_ieee_mode 1
		.amdhsa_fp16_overflow 0
		.amdhsa_tg_split 0
		.amdhsa_exception_fp_ieee_invalid_op 0
		.amdhsa_exception_fp_denorm_src 0
		.amdhsa_exception_fp_ieee_div_zero 0
		.amdhsa_exception_fp_ieee_overflow 0
		.amdhsa_exception_fp_ieee_underflow 0
		.amdhsa_exception_fp_ieee_inexact 0
		.amdhsa_exception_int_div_zero 0
	.end_amdhsa_kernel

; __global__ void __launch_bounds__(NTHR) mega(Args a) {
amdhsa.kernels:
  - .agpr_count:     0
    .args:
      - .offset:         0
        .size:           280
        .value_kind:     by_value
      - .offset:         280
        .size:           4
        .value_kind:     hidden_block_count_x
      - .offset:         284
        .size:           4
        .value_kind:     hidden_block_count_y
      - .offset:         288
        .size:           4
        .value_kind:     hidden_block_count_z
      - .offset:         292
        .size:           2
        .value_kind:     hidden_group_size_x
      - .offset:         294
        .size:           2
        .value_kind:     hidden_group_size_y
      - .offset:         296
        .size:           2
        .value_kind:     hidden_group_size_z
      - .offset:         298
        .size:           2
        .value_kind:     hidden_remainder_x
      - .offset:         300
        .size:           2
        .value_kind:     hidden_remainder_y
      - .offset:         302
        .size:           2
        .value_kind:     hidden_remainder_z
      - .offset:         320
        .size:           8
        .value_kind:     hidden_global_offset_x
      - .offset:         328
        .size:           8
        .value_kind:     hidden_global_offset_y
      - .offset:         336
        .size:           8
        .value_kind:     hidden_global_offset_z
      - .offset:         344
        .size:           2
        .value_kind:     hidden_grid_dims
      - .offset:         368
        .size:           8
        .value_kind:     hidden_multigrid_sync_arg
      - .offset:         400
        .size:           4
        .value_kind:     hidden_dynamic_lds_size
    .group_segment_fixed_size: 0
    .kernarg_segment_align: 8
    .kernarg_segment_size: 536
    .language:       OpenCL C
    .language_version:
      - 2
      - 0
    .max_flat_workgroup_size: 512
    .name:           _Z4mega4Args
    .private_segment_fixed_size: 0
    .sgpr_count:     108
    .sgpr_spill_count: 0
    .symbol:         _Z4mega4Args.kd
    .uniform_work_group_size: 1
    .uses_dynamic_stack: false
    .vgpr_count:     252
    .vgpr_spill_count: 0
    .wavefront_size: 64
